# prep mod item: silu(c) LDS fill - 8 serialized load-wait iterations replaced by 8 prefetched loads with counted vmcnt
# speedup vs baseline: 1.0115x; 1.0012x over previous
; DI void prep_phase(int ws, PP p, char* shm) {
;     ...
;       for (int i = tid; i < 4096; i += NTHR) {
;         float cv = p->c[i];
;         fs[i] = cv / (1.f + __expf(-cv));
;       }
.LBB0_35:
	global_load_dword v160, v[2:3], off
	v_lshl_add_u64 v[2:3], v[2:3], 0, s[36:37]
	global_load_dword v161, v[2:3], off
	v_lshl_add_u64 v[2:3], v[2:3], 0, s[36:37]
	global_load_dword v162, v[2:3], off
	v_lshl_add_u64 v[2:3], v[2:3], 0, s[36:37]
	global_load_dword v163, v[2:3], off
	v_lshl_add_u64 v[2:3], v[2:3], 0, s[36:37]
	global_load_dword v164, v[2:3], off
	v_lshl_add_u64 v[2:3], v[2:3], 0, s[36:37]
	global_load_dword v165, v[2:3], off
	v_lshl_add_u64 v[2:3], v[2:3], 0, s[36:37]
	global_load_dword v166, v[2:3], off
	v_lshl_add_u64 v[2:3], v[2:3], 0, s[36:37]
	global_load_dword v167, v[2:3], off
	v_lshl_add_u64 v[2:3], v[2:3], 0, s[36:37]
	s_waitcnt vmcnt(7)
	v_mov_b32_e32 v6, v160
	v_mul_f32_e32 v7, 0xbfb8aa3b, v6
	v_exp_f32_e32 v7, v7
	s_nop 0
	v_add_f32_e32 v7, 1.0, v7
	v_div_scale_f32 v8, s[18:19], v7, v7, v6
	v_rcp_f32_e32 v9, v8
	v_div_scale_f32 v10, vcc, v6, v7, v6
	v_fma_f32 v11, -v8, v9, 1.0
	v_fmac_f32_e32 v9, v11, v9
	v_mul_f32_e32 v11, v10, v9
	v_fma_f32 v12, -v8, v11, v10
	v_fmac_f32_e32 v11, v12, v9
	v_fma_f32 v8, -v8, v11, v10
	v_div_fmas_f32 v8, v8, v9, v11
	v_div_fixup_f32 v6, v8, v7, v6
	ds_write_b32 v4, v6
	v_add_u32_e32 v4, 0x800, v4
	s_waitcnt vmcnt(6)
	v_mov_b32_e32 v6, v161
	v_mul_f32_e32 v7, 0xbfb8aa3b, v6
	v_exp_f32_e32 v7, v7
	s_nop 0
	v_add_f32_e32 v7, 1.0, v7
	v_div_scale_f32 v8, s[18:19], v7, v7, v6
	v_rcp_f32_e32 v9, v8
	v_div_scale_f32 v10, vcc, v6, v7, v6
	v_fma_f32 v11, -v8, v9, 1.0
	v_fmac_f32_e32 v9, v11, v9
	v_mul_f32_e32 v11, v10, v9
	v_fma_f32 v12, -v8, v11, v10
	v_fmac_f32_e32 v11, v12, v9
	v_fma_f32 v8, -v8, v11, v10
	v_div_fmas_f32 v8, v8, v9, v11
	v_div_fixup_f32 v6, v8, v7, v6
	ds_write_b32 v4, v6
	v_add_u32_e32 v4, 0x800, v4
	s_waitcnt vmcnt(5)
	v_mov_b32_e32 v6, v162
	v_mul_f32_e32 v7, 0xbfb8aa3b, v6
	v_exp_f32_e32 v7, v7
	s_nop 0
	v_add_f32_e32 v7, 1.0, v7
	v_div_scale_f32 v8, s[18:19], v7, v7, v6
	v_rcp_f32_e32 v9, v8
	v_div_scale_f32 v10, vcc, v6, v7, v6
	v_fma_f32 v11, -v8, v9, 1.0
	v_fmac_f32_e32 v9, v11, v9
	v_mul_f32_e32 v11, v10, v9
	v_fma_f32 v12, -v8, v11, v10
	v_fmac_f32_e32 v11, v12, v9
	v_fma_f32 v8, -v8, v11, v10
	v_div_fmas_f32 v8, v8, v9, v11
	v_div_fixup_f32 v6, v8, v7, v6
	ds_write_b32 v4, v6
	v_add_u32_e32 v4, 0x800, v4
	s_waitcnt vmcnt(4)
	v_mov_b32_e32 v6, v163
	v_mul_f32_e32 v7, 0xbfb8aa3b, v6
	v_exp_f32_e32 v7, v7
	s_nop 0
	v_add_f32_e32 v7, 1.0, v7
	v_div_scale_f32 v8, s[18:19], v7, v7, v6
	v_rcp_f32_e32 v9, v8
	v_div_scale_f32 v10, vcc, v6, v7, v6
	v_fma_f32 v11, -v8, v9, 1.0
	v_fmac_f32_e32 v9, v11, v9
	v_mul_f32_e32 v11, v10, v9
	v_fma_f32 v12, -v8, v11, v10
	v_fmac_f32_e32 v11, v12, v9
	v_fma_f32 v8, -v8, v11, v10
	v_div_fmas_f32 v8, v8, v9, v11
	v_div_fixup_f32 v6, v8, v7, v6
	ds_write_b32 v4, v6
	v_add_u32_e32 v4, 0x800, v4
	s_waitcnt vmcnt(3)
	v_mov_b32_e32 v6, v164
	v_mul_f32_e32 v7, 0xbfb8aa3b, v6
	v_exp_f32_e32 v7, v7
	s_nop 0
	v_add_f32_e32 v7, 1.0, v7
	v_div_scale_f32 v8, s[18:19], v7, v7, v6
	v_rcp_f32_e32 v9, v8
	v_div_scale_f32 v10, vcc, v6, v7, v6
	v_fma_f32 v11, -v8, v9, 1.0
	v_fmac_f32_e32 v9, v11, v9
	v_mul_f32_e32 v11, v10, v9
	v_fma_f32 v12, -v8, v11, v10
	v_fmac_f32_e32 v11, v12, v9
	v_fma_f32 v8, -v8, v11, v10
	v_div_fmas_f32 v8, v8, v9, v11
	v_div_fixup_f32 v6, v8, v7, v6
	ds_write_b32 v4, v6
	v_add_u32_e32 v4, 0x800, v4
	s_waitcnt vmcnt(2)
	v_mov_b32_e32 v6, v165
	v_mul_f32_e32 v7, 0xbfb8aa3b, v6
	v_exp_f32_e32 v7, v7
	s_nop 0
	v_add_f32_e32 v7, 1.0, v7
	v_div_scale_f32 v8, s[18:19], v7, v7, v6
	v_rcp_f32_e32 v9, v8
	v_div_scale_f32 v10, vcc, v6, v7, v6
	v_fma_f32 v11, -v8, v9, 1.0
	v_fmac_f32_e32 v9, v11, v9
	v_mul_f32_e32 v11, v10, v9
	v_fma_f32 v12, -v8, v11, v10
	v_fmac_f32_e32 v11, v12, v9
	v_fma_f32 v8, -v8, v11, v10
	v_div_fmas_f32 v8, v8, v9, v11
	v_div_fixup_f32 v6, v8, v7, v6
	ds_write_b32 v4, v6
	v_add_u32_e32 v4, 0x800, v4
	s_waitcnt vmcnt(1)
	v_mov_b32_e32 v6, v166
	v_mul_f32_e32 v7, 0xbfb8aa3b, v6
	v_exp_f32_e32 v7, v7
	s_nop 0
	v_add_f32_e32 v7, 1.0, v7
	v_div_scale_f32 v8, s[18:19], v7, v7, v6
	v_rcp_f32_e32 v9, v8
	v_div_scale_f32 v10, vcc, v6, v7, v6
	v_fma_f32 v11, -v8, v9, 1.0
	v_fmac_f32_e32 v9, v11, v9
	v_mul_f32_e32 v11, v10, v9
	v_fma_f32 v12, -v8, v11, v10
	v_fmac_f32_e32 v11, v12, v9
	v_fma_f32 v8, -v8, v11, v10
	v_div_fmas_f32 v8, v8, v9, v11
	v_div_fixup_f32 v6, v8, v7, v6
	ds_write_b32 v4, v6
	v_add_u32_e32 v4, 0x800, v4
	s_waitcnt vmcnt(0)
	v_mov_b32_e32 v6, v167
	v_mul_f32_e32 v7, 0xbfb8aa3b, v6
	v_exp_f32_e32 v7, v7
	s_nop 0
	v_add_f32_e32 v7, 1.0, v7
	v_div_scale_f32 v8, s[18:19], v7, v7, v6
	v_rcp_f32_e32 v9, v8
	v_div_scale_f32 v10, vcc, v6, v7, v6
	v_fma_f32 v11, -v8, v9, 1.0
	v_fmac_f32_e32 v9, v11, v9
	v_mul_f32_e32 v11, v10, v9
	v_fma_f32 v12, -v8, v11, v10
	v_fmac_f32_e32 v11, v12, v9
	v_fma_f32 v8, -v8, v11, v10
	v_div_fmas_f32 v8, v8, v9, v11
	v_div_fixup_f32 v6, v8, v7, v6
	ds_write_b32 v4, v6
	v_add_u32_e32 v4, 0x800, v4
